# FoX unit queue: one global queue (longest query block first over all 64 b,h) instead of per-XCD queues with stealing
# baseline (speedup 1.0000x reference)
.Lq_init:
	s_add_u32 s90, s54, 0x80000
	s_addc_u32 s91, s55, 0
	s_getreg_b32 s92, hwreg(HW_REG_XCC_ID, 0, 4)
	s_and_b32 s92, s92, 0

.Lq_scan:
	s_mov_b64 exec, 1
	v_mbcnt_lo_u32_b32 v251, -1, 0
	v_lshlrev_b32_e32 v251, 6, v251
	global_load_dword v250, v251, s[90:91] sc1
	s_waitcnt vmcnt(0)
	v_cmp_gt_u32_e32 vcc, 0x400, v250
	s_mov_b32 s95, vcc_lo
	s_cmp_eq_u32 s95, 0
	s_cbranch_scc1 .Lq_none
	s_lshr_b32 s94, s95, s92
	s_lshl_b32 s94, s94, s92
	s_cmp_lg_u32 s94, 0
	s_cselect_b32 s95, s94, s95
	s_ff1_i32_b32 s92, s95
	s_mov_b64 exec, 1
	v_mov_b32_e32 v250, 1
	s_lshl_b32 s95, s92, 6
	v_mov_b32_e32 v251, s95
	global_atomic_add v250, v251, v250, s[90:91] sc0
	s_waitcnt vmcnt(0)
	v_readfirstlane_b32 s95, v250
	s_cmp_ge_u32 s95, 0x400
	s_cbranch_scc1 .Lq_scan
	s_lshl_b32 s94, s92, 16
	s_or_b32 s95, s95, s94
	s_branch .Lq_pub

.Lq_read:
	v_mov_b32_e32 v252, 0x1c000
	ds_read_b32 v250, v252
	s_waitcnt lgkmcnt(0)
	v_readfirstlane_b32 s95, v250
	s_barrier
	s_bitcmp1_b32 s95, 30
	s_cbranch_scc1 .Lq_fetch
	s_bitcmp1_b32 s95, 31
	s_cbranch_scc1 .LBB0_662
	s_lshr_b32 s92, s95, 16
	s_and_b32 s95, s95, 0xffff
	s_lshr_b32 s94, s95, 6
	s_sub_i32 s94, 15, s94
	s_and_b32 s88, s95, 63
	s_lshl_b32 s88, s88, 3

.Lq_fill_done:
.LBB0_646:
	v_mul_lo_u32 v157, v146, s45
	v_lshlrev_b32_e32 v158, 4, v0
	v_add3_u32 v0, 0, v157, v158
	s_waitcnt vmcnt(0)
	v_readfirstlane_b32 s96, v255
	s_cmp_lg_u32 s96, 0
	s_cbranch_scc1 .Lq_w1
	s_mov_b64 s[96:97], exec
	s_mov_b64 exec, 1
	s_lshl_b32 s95, s92, 16
	v_or_b32_e32 v251, s95, v250
	v_mov_b32_e32 v253, 0x40000000
	v_cmp_gt_u32_e32 vcc, 0x400, v250
	v_mov_b32_e32 v252, 0x1c000
	v_cndmask_b32_e32 v251, v253, v251, vcc
	ds_write_b32 v252, v251
	s_mov_b64 exec, s[96:97]
